# scan: static s_setprio 1 for waves 4-7 (the later token blocks: more score tiles and the second PV product)
# baseline (speedup 1.0000x reference)
; #define LAS __attribute__((address_space(3)))
; __device__ void scan_phase(LAS unsigned char* lds, const Params& p) {
;     const int tid = threadIdx.x, w = __builtin_amdgcn_readfirstlane(tid >> 6), lane = tid & 63, ln = lane & 15, lq = lane >> 4;
;     constexpr int QST = 136, VST = 36;
;     constexpr int OFF_KS = 17408, OFF_V = 34816, BUFB = 39424;
;     LAS bf16_t* Sr = (LAS bf16_t*)(lds + 2 * BUFB);
;     LAS float* scs = (LAS float*)(lds + 2 * BUFB + 9216);
;     bf16_t* O = (bf16_t*)p.out;
;     bf16_t* Odummy = (bf16_t*)(p.ws + WS_A) + (size_t)blockIdx.x * 64 * 512;
;     const float* RT = (const float*)(p.ws + WS_RT);
;     const int eb = w & 1, tb = w >> 1;
;     if (w >= 4) __builtin_amdgcn_s_setprio(1);
;     for (int item = blockIdx.x; item < 256; item += gridDim.x) {
;         const int seq = (item & 7) + 8 * (item >> 5), es = (item >> 3) & 3;
;         const int dir = seq & 1, h = (seq >> 1) & 3, b = seq >> 3;
;         const char* Qx = (const char*)((const bf16_t*)(p.ws + (dir ? WS_QB : WS_QF)) + h * 128);
;         const char* Kx = (const char*)((const bf16_t*)(p.ws + (dir ? WS_KB : WS_KF)) + h * 128);
;         const char* Vx = (const char*)((const bf16_t*)(p.ws + WS_V) + h * 128 + es * 32);
;         const char* Rx = (const char*)(RT + (size_t)dir * NCHUNK * 512 + h * 128);
;         const char* Tx = (const char*)(RT + (size_t)(2 + dir) * NCHUNK * 512 + h * 128);
;         const unsigned qoff0 = (unsigned)((dir ? 63 - (tid >> 4) : (tid >> 4)) * 1024 + (tid & 15) * 16), qstep = dir ? (unsigned)-32768 : 32768u;
;         const unsigned voff = (unsigned)((dir ? 63 - (tid >> 3) : (tid >> 3)) * 1024 + (tid & 7) * 8), roff = (unsigned)(tid & 127) * 4u;
.LBB0_256:
	s_cmp_lt_i32 s72, 4
	s_cselect_b64 s[8:9], -1, 0
	s_waitcnt lgkmcnt(0)
	s_and_b64 s[38:39], s[8:9], s[6:7]
	s_andn2_b64 vcc, exec, s[38:39]
	s_cbranch_vccnz .LBB0_308
	v_lshrrev_b32_e32 v1, 6, v0
	s_nop 0
	v_readfirstlane_b32 s6, v1
	s_lshr_b32 s7, s6, 1
	s_and_b32 s8, s6, 1
	s_mov_b32 s9, s2
	s_cmp_lt_u32 s6, 4
	s_cbranch_scc1 .Lsc5_noprio
	s_setprio 1
.Lsc5_noprio:
	s_load_dword s35, s[0:1], 0x98
	s_cmp_ge_u32 s7, 2
	s_cselect_b32 s11, 1, 0
	s_cmp_le_u32 s8, s7
	s_cselect_b32 s13, 1, 0
	s_add_u32 s3, s8, 2
	s_cmp_le_u32 s3, s7
	s_cselect_b32 s14, 1, 0
	v_and_b32_e32 v58, 15, v0
	v_bfe_u32 v59, v0, 4, 2
	v_lshrrev_b32_e32 v90, 2, v58
	v_and_b32_e32 v91, 3, v0
	v_and_b32_e32 v92, 63, v0
	v_lshlrev_b32_e32 v93, 2, v59
	v_add_u32_e32 v1, 0, v93
	v_cmp_le_u32_e64 s[94:95], v1, v58
	v_add_u32_e32 v1, 1, v93
	v_cmp_le_u32_e64 s[96:97], v1, v58
	v_add_u32_e32 v1, 2, v93
	v_cmp_le_u32_e64 s[98:99], v1, v58
	v_add_u32_e32 v1, 3, v93
	v_cmp_le_u32_e64 vcc, v1, v58
	s_cmp_eq_u32 s8, s7
	s_cselect_b64 s[76:77], s[94:95], -1
	s_cselect_b64 s[78:79], s[96:97], -1
	s_cselect_b64 s[80:81], s[98:99], -1
	s_cselect_b64 s[82:83], vcc, -1
	s_add_u32 s3, s8, 2
	s_cmp_eq_u32 s3, s7
	s_cselect_b64 s[84:85], s[94:95], -1
	s_cselect_b64 s[88:89], s[96:97], -1
	s_cselect_b64 s[90:91], s[98:99], -1
	s_cselect_b64 s[92:93], vcc, -1
	v_lshrrev_b32_e32 v1, 4, v0
	v_mul_u32_u24_e32 v60, 272, v1
	v_lshl_add_u32 v60, v58, 4, v60
	v_lshrrev_b32_e32 v1, 3, v0
	v_mul_u32_u24_e32 v63, 72, v1
	v_and_b32_e32 v1, 7, v0
	v_lshl_add_u32 v63, v1, 3, v63
	v_and_b32_e32 v1, 0x7f, v0
	v_lshlrev_b32_e32 v56, 2, v1
	s_cmp_lt_u32 s6, 2
	s_mov_b32 s4, 127488
	s_cselect_b32 s3, s4, 129024
	v_add_u32_e32 v78, s3, v56
	s_lshl_b32 s3, s7, 7
	s_add_u32 s3, s3, 127488
	v_lshl_add_u32 v79, v58, 2, s3
	s_mul_i32 s3, s7, 2304
	s_lshl_b32 s4, s8, 5
	s_add_u32 s3, s3, s4
	v_mul_u32_u24_e32 v1, 72, v58
	v_lshl_add_u32 v1, v59, 3, v1
	v_add_u32_e32 v1, s3, v1
	v_add_u32_e32 v80, 118272, v1
	v_add_u32_e32 v81, 131088, v1
	s_mul_i32 s3, s8, 4352
	v_mul_u32_u24_e32 v69, 272, v58
	v_lshl_add_u32 v69, v59, 4, v69
	v_add_u32_e32 v69, s3, v69
	s_mul_i32 s3, s7, 4352
	v_mul_u32_u24_e32 v66, 272, v58
	v_lshl_add_u32 v66, v59, 4, v66
	v_add_u32_e32 v66, s3, v66
	s_lshl_b32 s3, s7, 11
	v_lshl_add_u32 v1, v92, 4, s3
	s_lshl_b32 s4, s8, 3
	v_add_u32_e32 v86, 140304, v1
	v_add_u32_e32 v84, s4, v86
	v_add_u32_e32 v87, 148496, v1
	v_add_u32_e32 v85, s4, v87
	v_lshl_add_u32 v1, v59, 3, v90
	v_mul_u32_u24_e32 v1, 72, v1
	v_lshl_add_u32 v1, v91, 3, v1
	s_lshl_b32 s4, s8, 5
	v_add_u32_e32 v1, s4, v1
	v_add_u32_e32 v82, 118272, v1
	v_add_u32_e32 v83, 131088, v1
	v_lshl_add_u32 v1, v59, 2, v90
	v_mul_u32_u24_e32 v72, 72, v1
	v_lshl_add_u32 v72, v91, 3, v72
	v_add_u32_e32 v72, s4, v72
	v_mul_u32_u24_e32 v75, 272, v1
	v_lshl_add_u32 v75, v91, 3, v75
	s_lshl_b32 s3, s7, 6
	v_add_u32_e32 v75, s3, v75
	v_add_u32_e32 v61, 39424, v60
	v_add_u32_e32 v62, 78848, v60
	v_add_u32_e32 v64, 39424, v63
	v_add_u32_e32 v65, 78848, v63
	v_add_u32_e32 v67, 39424, v66
	v_add_u32_e32 v68, 78848, v66
	v_add_u32_e32 v70, 39424, v69
	v_add_u32_e32 v71, 78848, v69
	v_add_u32_e32 v73, 39424, v72
	v_add_u32_e32 v74, 78848, v72
	v_add_u32_e32 v76, 39424, v75
	v_add_u32_e32 v77, 78848, v75
	s_waitcnt lgkmcnt(0)
	s_cmp_gt_u32 s9, 0xff
	s_cbranch_scc1 .Lsc5_done
